# v10 + prologue weight transposes: all 32 loads of an item in flight (were one at a time)
# speedup vs baseline: 1.0121x; 1.0092x over previous
.LBB0_10:
.LBB0_11:
	v_cmp_ne_u32_e64 s[2:3], 1, v49
	s_andn2_b64 vcc, exec, s[8:9]
	v_mov_b32_e32 v72, 0
	v_mov_b32_e32 v73, 0
	v_mov_b32_e32 v74, 0
	v_mov_b32_e32 v75, 0
	v_mov_b32_e32 v76, 0
	v_mov_b32_e32 v77, 0
	v_mov_b32_e32 v78, 0
	v_mov_b32_e32 v79, 0
	v_mov_b32_e32 v80, 0
	v_mov_b32_e32 v81, 0
	v_mov_b32_e32 v82, 0
	v_mov_b32_e32 v83, 0
	v_mov_b32_e32 v84, 0
	v_mov_b32_e32 v85, 0
	v_mov_b32_e32 v86, 0
	v_mov_b32_e32 v87, 0
	v_mov_b32_e32 v88, 0
	v_mov_b32_e32 v89, 0
	v_mov_b32_e32 v90, 0
	v_mov_b32_e32 v91, 0
	v_mov_b32_e32 v92, 0
	v_mov_b32_e32 v93, 0
	v_mov_b32_e32 v94, 0
	v_mov_b32_e32 v95, 0
	v_mov_b32_e32 v96, 0
	v_mov_b32_e32 v97, 0
	v_mov_b32_e32 v98, 0
	v_mov_b32_e32 v99, 0
	v_mov_b32_e32 v100, 0
	v_mov_b32_e32 v101, 0
	v_mov_b32_e32 v102, 0
	v_mov_b32_e32 v103, 0
	s_cbranch_vccnz .Ltr0_skip
	v_lshl_add_u64 v[70:71], v[32:33], 0, s[16:17]
	global_load_dword v72, v[70:71], off
	v_lshl_add_u64 v[70:71], v[30:31], 0, s[16:17]
	global_load_dword v73, v[70:71], off
	v_lshl_add_u64 v[70:71], v[28:29], 0, s[16:17]
	global_load_dword v74, v[70:71], off
	v_lshl_add_u64 v[70:71], v[24:25], 0, s[16:17]
	global_load_dword v75, v[70:71], off
	v_lshl_add_u64 v[70:71], v[22:23], 0, s[16:17]
	global_load_dword v76, v[70:71], off
	v_lshl_add_u64 v[70:71], v[20:21], 0, s[16:17]
	global_load_dword v77, v[70:71], off
	v_lshl_add_u64 v[70:71], v[18:19], 0, s[16:17]
	global_load_dword v78, v[70:71], off
	v_lshl_add_u64 v[70:71], v[16:17], 0, s[16:17]
	global_load_dword v79, v[70:71], off
	s_add_u32 s16, s16, 0x10000
	s_addc_u32 s17, s17, 0
	v_lshl_add_u64 v[70:71], v[32:33], 0, s[16:17]
	global_load_dword v80, v[70:71], off
	v_lshl_add_u64 v[70:71], v[30:31], 0, s[16:17]
	global_load_dword v81, v[70:71], off
	v_lshl_add_u64 v[70:71], v[28:29], 0, s[16:17]
	global_load_dword v82, v[70:71], off
	v_lshl_add_u64 v[70:71], v[24:25], 0, s[16:17]
	global_load_dword v83, v[70:71], off
	v_lshl_add_u64 v[70:71], v[22:23], 0, s[16:17]
	global_load_dword v84, v[70:71], off
	v_lshl_add_u64 v[70:71], v[20:21], 0, s[16:17]
	global_load_dword v85, v[70:71], off
	v_lshl_add_u64 v[70:71], v[18:19], 0, s[16:17]
	global_load_dword v86, v[70:71], off
	v_lshl_add_u64 v[70:71], v[16:17], 0, s[16:17]
	global_load_dword v87, v[70:71], off
	s_add_u32 s16, s16, 0x10000
	s_addc_u32 s17, s17, 0
	v_lshl_add_u64 v[70:71], v[32:33], 0, s[16:17]
	global_load_dword v88, v[70:71], off
	v_lshl_add_u64 v[70:71], v[30:31], 0, s[16:17]
	global_load_dword v89, v[70:71], off
	v_lshl_add_u64 v[70:71], v[28:29], 0, s[16:17]
	global_load_dword v90, v[70:71], off
	v_lshl_add_u64 v[70:71], v[24:25], 0, s[16:17]
	global_load_dword v91, v[70:71], off
	v_lshl_add_u64 v[70:71], v[22:23], 0, s[16:17]
	global_load_dword v92, v[70:71], off
	v_lshl_add_u64 v[70:71], v[20:21], 0, s[16:17]
	global_load_dword v93, v[70:71], off
	v_lshl_add_u64 v[70:71], v[18:19], 0, s[16:17]
	global_load_dword v94, v[70:71], off
	v_lshl_add_u64 v[70:71], v[16:17], 0, s[16:17]
	global_load_dword v95, v[70:71], off
	s_add_u32 s16, s16, 0x10000
	s_addc_u32 s17, s17, 0
	v_lshl_add_u64 v[70:71], v[32:33], 0, s[16:17]
	global_load_dword v96, v[70:71], off
	v_lshl_add_u64 v[70:71], v[30:31], 0, s[16:17]
	global_load_dword v97, v[70:71], off
	v_lshl_add_u64 v[70:71], v[28:29], 0, s[16:17]
	global_load_dword v98, v[70:71], off
	v_lshl_add_u64 v[70:71], v[24:25], 0, s[16:17]
	global_load_dword v99, v[70:71], off
	v_lshl_add_u64 v[70:71], v[22:23], 0, s[16:17]
	global_load_dword v100, v[70:71], off
	v_lshl_add_u64 v[70:71], v[20:21], 0, s[16:17]
	global_load_dword v101, v[70:71], off
	v_lshl_add_u64 v[70:71], v[18:19], 0, s[16:17]
	global_load_dword v102, v[70:71], off
	v_lshl_add_u64 v[70:71], v[16:17], 0, s[16:17]
	global_load_dword v103, v[70:71], off
.Ltr0_skip:
	s_waitcnt vmcnt(0)
	ds_write_b32 v2, v72
	ds_write_b32 v2, v73 offset:264
	ds_write_b32 v2, v74 offset:528
	ds_write_b32 v2, v75 offset:792
	ds_write_b32 v2, v76 offset:1056
	ds_write_b32 v2, v77 offset:1320
	ds_write_b32 v2, v78 offset:1584
	ds_write_b32 v2, v79 offset:1848
	ds_write_b32 v2, v80 offset:2112
	ds_write_b32 v2, v81 offset:2376
	ds_write_b32 v2, v82 offset:2640
	ds_write_b32 v2, v83 offset:2904
	ds_write_b32 v2, v84 offset:3168
	ds_write_b32 v2, v85 offset:3432
	ds_write_b32 v2, v86 offset:3696
	ds_write_b32 v2, v87 offset:3960
	ds_write_b32 v2, v88 offset:4224
	ds_write_b32 v2, v89 offset:4488
	ds_write_b32 v2, v90 offset:4752
	ds_write_b32 v2, v91 offset:5016
	ds_write_b32 v2, v92 offset:5280
	ds_write_b32 v2, v93 offset:5544
	ds_write_b32 v2, v94 offset:5808
	ds_write_b32 v2, v95 offset:6072
	ds_write_b32 v2, v96 offset:6336
	ds_write_b32 v2, v97 offset:6600
	ds_write_b32 v2, v98 offset:6864
	ds_write_b32 v2, v99 offset:7128
	ds_write_b32 v2, v100 offset:7392
	ds_write_b32 v2, v101 offset:7656
	ds_write_b32 v2, v102 offset:7920
	ds_write_b32 v2, v103 offset:8184
	v_add_u32_e32 v2, 0x2100, v2
	s_mov_b32 s16, 0x40000
	s_mov_b32 s17, 0
	s_branch .LBB0_27

.LBB0_30:
.LBB0_31:
	v_mov_b32_e32 v72, 0
	v_mov_b32_e32 v73, 0
	v_mov_b32_e32 v74, 0
	v_mov_b32_e32 v75, 0
	v_mov_b32_e32 v76, 0
	v_mov_b32_e32 v77, 0
	v_mov_b32_e32 v78, 0
	v_mov_b32_e32 v79, 0
	v_mov_b32_e32 v80, 0
	v_mov_b32_e32 v81, 0
	v_mov_b32_e32 v82, 0
	v_mov_b32_e32 v83, 0
	v_mov_b32_e32 v84, 0
	v_mov_b32_e32 v85, 0
	v_mov_b32_e32 v86, 0
	v_mov_b32_e32 v87, 0
	v_mov_b32_e32 v88, 0
	v_mov_b32_e32 v89, 0
	v_mov_b32_e32 v90, 0
	v_mov_b32_e32 v91, 0
	v_mov_b32_e32 v92, 0
	v_mov_b32_e32 v93, 0
	v_mov_b32_e32 v94, 0
	v_mov_b32_e32 v95, 0
	v_mov_b32_e32 v96, 0
	v_mov_b32_e32 v97, 0
	v_mov_b32_e32 v98, 0
	v_mov_b32_e32 v99, 0
	v_mov_b32_e32 v100, 0
	v_mov_b32_e32 v101, 0
	v_mov_b32_e32 v102, 0
	v_mov_b32_e32 v103, 0
	s_and_saveexec_b64 s[16:17], vcc
	s_cbranch_execz .Ltr1_skip
	v_lshl_add_u64 v[70:71], v[32:33], 0, s[2:3]
	global_load_dword v72, v[70:71], off
	v_lshl_add_u64 v[70:71], v[30:31], 0, s[2:3]
	global_load_dword v73, v[70:71], off
	v_lshl_add_u64 v[70:71], v[28:29], 0, s[2:3]
	global_load_dword v74, v[70:71], off
	v_lshl_add_u64 v[70:71], v[24:25], 0, s[2:3]
	global_load_dword v75, v[70:71], off
	v_lshl_add_u64 v[70:71], v[22:23], 0, s[2:3]
	global_load_dword v76, v[70:71], off
	v_lshl_add_u64 v[70:71], v[20:21], 0, s[2:3]
	global_load_dword v77, v[70:71], off
	v_lshl_add_u64 v[70:71], v[18:19], 0, s[2:3]
	global_load_dword v78, v[70:71], off
	v_lshl_add_u64 v[70:71], v[16:17], 0, s[2:3]
	global_load_dword v79, v[70:71], off
	s_add_u32 s2, s2, 0x2c000
	s_addc_u32 s3, s3, 0
	v_lshl_add_u64 v[70:71], v[32:33], 0, s[2:3]
	global_load_dword v80, v[70:71], off
	v_lshl_add_u64 v[70:71], v[30:31], 0, s[2:3]
	global_load_dword v81, v[70:71], off
	v_lshl_add_u64 v[70:71], v[28:29], 0, s[2:3]
	global_load_dword v82, v[70:71], off
	v_lshl_add_u64 v[70:71], v[24:25], 0, s[2:3]
	global_load_dword v83, v[70:71], off
	v_lshl_add_u64 v[70:71], v[22:23], 0, s[2:3]
	global_load_dword v84, v[70:71], off
	v_lshl_add_u64 v[70:71], v[20:21], 0, s[2:3]
	global_load_dword v85, v[70:71], off
	v_lshl_add_u64 v[70:71], v[18:19], 0, s[2:3]
	global_load_dword v86, v[70:71], off
	v_lshl_add_u64 v[70:71], v[16:17], 0, s[2:3]
	global_load_dword v87, v[70:71], off
	s_add_u32 s2, s2, 0x2c000
	s_addc_u32 s3, s3, 0
	v_lshl_add_u64 v[70:71], v[32:33], 0, s[2:3]
	global_load_dword v88, v[70:71], off
	v_lshl_add_u64 v[70:71], v[30:31], 0, s[2:3]
	global_load_dword v89, v[70:71], off
	v_lshl_add_u64 v[70:71], v[28:29], 0, s[2:3]
	global_load_dword v90, v[70:71], off
	v_lshl_add_u64 v[70:71], v[24:25], 0, s[2:3]
	global_load_dword v91, v[70:71], off
	v_lshl_add_u64 v[70:71], v[22:23], 0, s[2:3]
	global_load_dword v92, v[70:71], off
	v_lshl_add_u64 v[70:71], v[20:21], 0, s[2:3]
	global_load_dword v93, v[70:71], off
	v_lshl_add_u64 v[70:71], v[18:19], 0, s[2:3]
	global_load_dword v94, v[70:71], off
	v_lshl_add_u64 v[70:71], v[16:17], 0, s[2:3]
	global_load_dword v95, v[70:71], off
	s_add_u32 s2, s2, 0x2c000
	s_addc_u32 s3, s3, 0
	v_lshl_add_u64 v[70:71], v[32:33], 0, s[2:3]
	global_load_dword v96, v[70:71], off
	v_lshl_add_u64 v[70:71], v[30:31], 0, s[2:3]
	global_load_dword v97, v[70:71], off
	v_lshl_add_u64 v[70:71], v[28:29], 0, s[2:3]
	global_load_dword v98, v[70:71], off
	v_lshl_add_u64 v[70:71], v[24:25], 0, s[2:3]
	global_load_dword v99, v[70:71], off
	v_lshl_add_u64 v[70:71], v[22:23], 0, s[2:3]
	global_load_dword v100, v[70:71], off
	v_lshl_add_u64 v[70:71], v[20:21], 0, s[2:3]
	global_load_dword v101, v[70:71], off
	v_lshl_add_u64 v[70:71], v[18:19], 0, s[2:3]
	global_load_dword v102, v[70:71], off
	v_lshl_add_u64 v[70:71], v[16:17], 0, s[2:3]
	global_load_dword v103, v[70:71], off
.Ltr1_skip:
	s_or_b64 exec, exec, s[16:17]
	s_waitcnt vmcnt(0)
	ds_write_b32 v2, v72
	ds_write_b32 v2, v73 offset:264
	ds_write_b32 v2, v74 offset:528
	ds_write_b32 v2, v75 offset:792
	ds_write_b32 v2, v76 offset:1056
	ds_write_b32 v2, v77 offset:1320
	ds_write_b32 v2, v78 offset:1584
	ds_write_b32 v2, v79 offset:1848
	ds_write_b32 v2, v80 offset:2112
	ds_write_b32 v2, v81 offset:2376
	ds_write_b32 v2, v82 offset:2640
	ds_write_b32 v2, v83 offset:2904
	ds_write_b32 v2, v84 offset:3168
	ds_write_b32 v2, v85 offset:3432
	ds_write_b32 v2, v86 offset:3696
	ds_write_b32 v2, v87 offset:3960
	ds_write_b32 v2, v88 offset:4224
	ds_write_b32 v2, v89 offset:4488
	ds_write_b32 v2, v90 offset:4752
	ds_write_b32 v2, v91 offset:5016
	ds_write_b32 v2, v92 offset:5280
	ds_write_b32 v2, v93 offset:5544
	ds_write_b32 v2, v94 offset:5808
	ds_write_b32 v2, v95 offset:6072
	ds_write_b32 v2, v96 offset:6336
	ds_write_b32 v2, v97 offset:6600
	ds_write_b32 v2, v98 offset:6864
	ds_write_b32 v2, v99 offset:7128
	ds_write_b32 v2, v100 offset:7392
	ds_write_b32 v2, v101 offset:7656
	ds_write_b32 v2, v102 offset:7920
	ds_write_b32 v2, v103 offset:8184
	v_add_u32_e32 v2, 0x2100, v2
	s_mov_b32 s2, 0xb0000
	s_mov_b32 s3, 0
	s_branch .LBB0_47

.LBB0_51:
.LBB0_52:
	v_cndmask_b32_e64 v59, 0, 1, s[10:11]
	v_cmp_ne_u32_e64 s[2:3], 1, v59
	s_andn2_b64 vcc, exec, s[10:11]
	v_mov_b32_e32 v72, 0
	v_mov_b32_e32 v73, 0
	v_mov_b32_e32 v74, 0
	v_mov_b32_e32 v75, 0
	v_mov_b32_e32 v76, 0
	v_mov_b32_e32 v77, 0
	v_mov_b32_e32 v78, 0
	v_mov_b32_e32 v79, 0
	v_mov_b32_e32 v80, 0
	v_mov_b32_e32 v81, 0
	v_mov_b32_e32 v82, 0
	v_mov_b32_e32 v83, 0
	v_mov_b32_e32 v84, 0
	v_mov_b32_e32 v85, 0
	v_mov_b32_e32 v86, 0
	v_mov_b32_e32 v87, 0
	v_mov_b32_e32 v88, 0
	v_mov_b32_e32 v89, 0
	v_mov_b32_e32 v90, 0
	v_mov_b32_e32 v91, 0
	v_mov_b32_e32 v92, 0
	v_mov_b32_e32 v93, 0
	v_mov_b32_e32 v94, 0
	v_mov_b32_e32 v95, 0
	v_mov_b32_e32 v96, 0
	v_mov_b32_e32 v97, 0
	v_mov_b32_e32 v98, 0
	v_mov_b32_e32 v99, 0
	v_mov_b32_e32 v100, 0
	v_mov_b32_e32 v101, 0
	v_mov_b32_e32 v102, 0
	v_mov_b32_e32 v103, 0
	s_cbranch_vccnz .Ltr2_skip
	v_lshl_add_u64 v[70:71], v[32:33], 0, s[16:17]
	global_load_dword v72, v[70:71], off
	v_lshl_add_u64 v[70:71], v[30:31], 0, s[16:17]
	global_load_dword v73, v[70:71], off
	v_lshl_add_u64 v[70:71], v[28:29], 0, s[16:17]
	global_load_dword v74, v[70:71], off
	v_lshl_add_u64 v[70:71], v[24:25], 0, s[16:17]
	global_load_dword v75, v[70:71], off
	v_lshl_add_u64 v[70:71], v[22:23], 0, s[16:17]
	global_load_dword v76, v[70:71], off
	v_lshl_add_u64 v[70:71], v[20:21], 0, s[16:17]
	global_load_dword v77, v[70:71], off
	v_lshl_add_u64 v[70:71], v[18:19], 0, s[16:17]
	global_load_dword v78, v[70:71], off
	v_lshl_add_u64 v[70:71], v[16:17], 0, s[16:17]
	global_load_dword v79, v[70:71], off
	s_add_u32 s16, s16, 0x10000
	s_addc_u32 s17, s17, 0
	v_lshl_add_u64 v[70:71], v[32:33], 0, s[16:17]
	global_load_dword v80, v[70:71], off
	v_lshl_add_u64 v[70:71], v[30:31], 0, s[16:17]
	global_load_dword v81, v[70:71], off
	v_lshl_add_u64 v[70:71], v[28:29], 0, s[16:17]
	global_load_dword v82, v[70:71], off
	v_lshl_add_u64 v[70:71], v[24:25], 0, s[16:17]
	global_load_dword v83, v[70:71], off
	v_lshl_add_u64 v[70:71], v[22:23], 0, s[16:17]
	global_load_dword v84, v[70:71], off
	v_lshl_add_u64 v[70:71], v[20:21], 0, s[16:17]
	global_load_dword v85, v[70:71], off
	v_lshl_add_u64 v[70:71], v[18:19], 0, s[16:17]
	global_load_dword v86, v[70:71], off
	v_lshl_add_u64 v[70:71], v[16:17], 0, s[16:17]
	global_load_dword v87, v[70:71], off
	s_add_u32 s16, s16, 0x10000
	s_addc_u32 s17, s17, 0
	v_lshl_add_u64 v[70:71], v[32:33], 0, s[16:17]
	global_load_dword v88, v[70:71], off
	v_lshl_add_u64 v[70:71], v[30:31], 0, s[16:17]
	global_load_dword v89, v[70:71], off
	v_lshl_add_u64 v[70:71], v[28:29], 0, s[16:17]
	global_load_dword v90, v[70:71], off
	v_lshl_add_u64 v[70:71], v[24:25], 0, s[16:17]
	global_load_dword v91, v[70:71], off
	v_lshl_add_u64 v[70:71], v[22:23], 0, s[16:17]
	global_load_dword v92, v[70:71], off
	v_lshl_add_u64 v[70:71], v[20:21], 0, s[16:17]
	global_load_dword v93, v[70:71], off
	v_lshl_add_u64 v[70:71], v[18:19], 0, s[16:17]
	global_load_dword v94, v[70:71], off
	v_lshl_add_u64 v[70:71], v[16:17], 0, s[16:17]
	global_load_dword v95, v[70:71], off
	s_add_u32 s16, s16, 0x10000
	s_addc_u32 s17, s17, 0
	v_lshl_add_u64 v[70:71], v[32:33], 0, s[16:17]
	global_load_dword v96, v[70:71], off
	v_lshl_add_u64 v[70:71], v[30:31], 0, s[16:17]
	global_load_dword v97, v[70:71], off
	v_lshl_add_u64 v[70:71], v[28:29], 0, s[16:17]
	global_load_dword v98, v[70:71], off
	v_lshl_add_u64 v[70:71], v[24:25], 0, s[16:17]
	global_load_dword v99, v[70:71], off
	v_lshl_add_u64 v[70:71], v[22:23], 0, s[16:17]
	global_load_dword v100, v[70:71], off
	v_lshl_add_u64 v[70:71], v[20:21], 0, s[16:17]
	global_load_dword v101, v[70:71], off
	v_lshl_add_u64 v[70:71], v[18:19], 0, s[16:17]
	global_load_dword v102, v[70:71], off
	v_lshl_add_u64 v[70:71], v[16:17], 0, s[16:17]
	global_load_dword v103, v[70:71], off

.LBB0_82:
.LBB0_83:
	v_mov_b32_e32 v72, 0
	v_mov_b32_e32 v73, 0
	v_mov_b32_e32 v74, 0
	v_mov_b32_e32 v75, 0
	v_mov_b32_e32 v76, 0
	v_mov_b32_e32 v77, 0
	v_mov_b32_e32 v78, 0
	v_mov_b32_e32 v79, 0
	v_mov_b32_e32 v80, 0
	v_mov_b32_e32 v81, 0
	v_mov_b32_e32 v82, 0
	v_mov_b32_e32 v83, 0
	v_mov_b32_e32 v84, 0
	v_mov_b32_e32 v85, 0
	v_mov_b32_e32 v86, 0
	v_mov_b32_e32 v87, 0
	v_mov_b32_e32 v88, 0
	v_mov_b32_e32 v89, 0
	v_mov_b32_e32 v90, 0
	v_mov_b32_e32 v91, 0
	v_mov_b32_e32 v92, 0
	v_mov_b32_e32 v93, 0
	v_mov_b32_e32 v94, 0
	v_mov_b32_e32 v95, 0
	v_mov_b32_e32 v96, 0
	v_mov_b32_e32 v97, 0
	v_mov_b32_e32 v98, 0
	v_mov_b32_e32 v99, 0
	v_mov_b32_e32 v100, 0
	v_mov_b32_e32 v101, 0
	v_mov_b32_e32 v102, 0
	v_mov_b32_e32 v103, 0
	s_and_saveexec_b64 s[18:19], s[2:3]
	s_cbranch_execz .Ltr3_skip
	v_lshl_add_u64 v[70:71], v[32:33], 0, s[16:17]
	global_load_dword v72, v[70:71], off
	v_lshl_add_u64 v[70:71], v[30:31], 0, s[16:17]
	global_load_dword v73, v[70:71], off
	v_lshl_add_u64 v[70:71], v[28:29], 0, s[16:17]
	global_load_dword v74, v[70:71], off
	v_lshl_add_u64 v[70:71], v[24:25], 0, s[16:17]
	global_load_dword v75, v[70:71], off
	v_lshl_add_u64 v[70:71], v[22:23], 0, s[16:17]
	global_load_dword v76, v[70:71], off
	v_lshl_add_u64 v[70:71], v[20:21], 0, s[16:17]
	global_load_dword v77, v[70:71], off
	v_lshl_add_u64 v[70:71], v[18:19], 0, s[16:17]
	global_load_dword v78, v[70:71], off
	v_lshl_add_u64 v[70:71], v[16:17], 0, s[16:17]
	global_load_dword v79, v[70:71], off
	s_add_u32 s16, s16, 0x29300
	s_addc_u32 s17, s17, 0
	v_lshl_add_u64 v[70:71], v[32:33], 0, s[16:17]
	global_load_dword v80, v[70:71], off
	v_lshl_add_u64 v[70:71], v[30:31], 0, s[16:17]
	global_load_dword v81, v[70:71], off
	v_lshl_add_u64 v[70:71], v[28:29], 0, s[16:17]
	global_load_dword v82, v[70:71], off
	v_lshl_add_u64 v[70:71], v[24:25], 0, s[16:17]
	global_load_dword v83, v[70:71], off
	v_lshl_add_u64 v[70:71], v[22:23], 0, s[16:17]
	global_load_dword v84, v[70:71], off
	v_lshl_add_u64 v[70:71], v[20:21], 0, s[16:17]
	global_load_dword v85, v[70:71], off
	v_lshl_add_u64 v[70:71], v[18:19], 0, s[16:17]
	global_load_dword v86, v[70:71], off
	v_lshl_add_u64 v[70:71], v[16:17], 0, s[16:17]
	global_load_dword v87, v[70:71], off
	s_add_u32 s16, s16, 0x29300
	s_addc_u32 s17, s17, 0
	v_lshl_add_u64 v[70:71], v[32:33], 0, s[16:17]
	global_load_dword v88, v[70:71], off
	v_lshl_add_u64 v[70:71], v[30:31], 0, s[16:17]
	global_load_dword v89, v[70:71], off
	v_lshl_add_u64 v[70:71], v[28:29], 0, s[16:17]
	global_load_dword v90, v[70:71], off
	v_lshl_add_u64 v[70:71], v[24:25], 0, s[16:17]
	global_load_dword v91, v[70:71], off
	v_lshl_add_u64 v[70:71], v[22:23], 0, s[16:17]
	global_load_dword v92, v[70:71], off
	v_lshl_add_u64 v[70:71], v[20:21], 0, s[16:17]
	global_load_dword v93, v[70:71], off
	v_lshl_add_u64 v[70:71], v[18:19], 0, s[16:17]
	global_load_dword v94, v[70:71], off
	v_lshl_add_u64 v[70:71], v[16:17], 0, s[16:17]
	global_load_dword v95, v[70:71], off
	s_add_u32 s16, s16, 0x29300
	s_addc_u32 s17, s17, 0
	v_lshl_add_u64 v[70:71], v[32:33], 0, s[16:17]
	global_load_dword v96, v[70:71], off
	v_lshl_add_u64 v[70:71], v[30:31], 0, s[16:17]
	global_load_dword v97, v[70:71], off
	v_lshl_add_u64 v[70:71], v[28:29], 0, s[16:17]
	global_load_dword v98, v[70:71], off
	v_lshl_add_u64 v[70:71], v[24:25], 0, s[16:17]
	global_load_dword v99, v[70:71], off
	v_lshl_add_u64 v[70:71], v[22:23], 0, s[16:17]
	global_load_dword v100, v[70:71], off
	v_lshl_add_u64 v[70:71], v[20:21], 0, s[16:17]
	global_load_dword v101, v[70:71], off
	v_lshl_add_u64 v[70:71], v[18:19], 0, s[16:17]
	global_load_dword v102, v[70:71], off
	v_lshl_add_u64 v[70:71], v[16:17], 0, s[16:17]
	global_load_dword v103, v[70:71], off
.Ltr3_skip:
	s_or_b64 exec, exec, s[18:19]
	s_waitcnt vmcnt(0)
	ds_write_b32 v2, v72
	ds_write_b32 v2, v73 offset:264
	ds_write_b32 v2, v74 offset:528
	ds_write_b32 v2, v75 offset:792
	ds_write_b32 v2, v76 offset:1056
	ds_write_b32 v2, v77 offset:1320
	ds_write_b32 v2, v78 offset:1584
	ds_write_b32 v2, v79 offset:1848
	ds_write_b32 v2, v80 offset:2112
	ds_write_b32 v2, v81 offset:2376
	ds_write_b32 v2, v82 offset:2640
	ds_write_b32 v2, v83 offset:2904
	ds_write_b32 v2, v84 offset:3168
	ds_write_b32 v2, v85 offset:3432
	ds_write_b32 v2, v86 offset:3696
	ds_write_b32 v2, v87 offset:3960
	ds_write_b32 v2, v88 offset:4224
	ds_write_b32 v2, v89 offset:4488
	ds_write_b32 v2, v90 offset:4752
	ds_write_b32 v2, v91 offset:5016
	ds_write_b32 v2, v92 offset:5280
	ds_write_b32 v2, v93 offset:5544
	ds_write_b32 v2, v94 offset:5808
	ds_write_b32 v2, v95 offset:6072
	ds_write_b32 v2, v96 offset:6336
	ds_write_b32 v2, v97 offset:6600
	ds_write_b32 v2, v98 offset:6864
	ds_write_b32 v2, v99 offset:7128
	ds_write_b32 v2, v100 offset:7392
	ds_write_b32 v2, v101 offset:7656
	ds_write_b32 v2, v102 offset:7920
	ds_write_b32 v2, v103 offset:8184
	v_add_u32_e32 v2, 0x2100, v2
	s_mov_b32 s16, 0xa4c00
	s_mov_b32 s17, 0
	s_branch .LBB0_4
